# final rmsnorm rows remapped to the owning block group so the last barrier is group-local too (8 of 14 barriers local)
# speedup vs baseline: 1.0194x; 1.0004x over previous
.LBB0_630:
	s_mov_b64 s[4:5], 0xb8fb000
	s_getreg_b32 s6, hwreg(HW_REG_XCC_ID, 0, 4)
	v_mbcnt_lo_u32_b32 v0, -1, 0
	v_mbcnt_hi_u32_b32 v0, -1, v0
	s_waitcnt vmcnt(0)
	s_waitcnt lgkmcnt(0)
	v_sub_u32_e32 v0, 0, v0
	v_cmp_eq_u32_e32 vcc, s3, v0
	s_barrier
	s_and_saveexec_b64 s[0:1], vcc
	s_cbranch_execz .LBB0_186
	v_mov_b32_e32 v2, 0x23808
	s_waitcnt vmcnt(0) lgkmcnt(0)
	ds_read_b32 v2, v2
	s_add_u32 s8, s28, s4
	s_addc_u32 s9, s29, s5
	s_waitcnt lgkmcnt(0)
	v_readfirstlane_b32 s10, v2
	s_cmp_eq_u32 s10, 0
	s_cbranch_scc1 .Lgs2_global
	s_and_b32 s10, s85, 7
	s_lshl_b32 s10, s10, 8
	s_add_i32 s10, s10, 0x480
	v_mov_b32_e32 v3, s10
	v_mov_b32_e32 v4, 1
	v_mov_b32_e32 v5, 0x100
	global_atomic_add v6, v3, v4, s[8:9] sc0
	s_waitcnt vmcnt(0)
	v_and_b32_e32 v6, 0xffffffe0, v6
	v_add_u32_e32 v6, 32, v6
	s_mov_b32 s11, 0

.LBB0_681:
	v_mbcnt_lo_u32_b32 v0, -1, 0
	v_mbcnt_hi_u32_b32 v0, -1, v0
	v_readlane_b32 s0, v254, 59
	v_mov_b32_e32 v2, 0x23808
	ds_read_b32 v2, v2
	s_waitcnt lgkmcnt(0)
	v_readfirstlane_b32 s4, v2
	s_cmp_eq_u32 s4, 0
	s_cbranch_scc1 .Lfin_map_done
	s_and_b32 s4, s85, 7
	s_lshl_b32 s4, s4, 8
	s_lshr_b32 s5, s85, 3
	s_lshl_b32 s5, s5, 3
	s_add_i32 s0, s4, s5
.Lfin_map_done:
	v_add_u32_e32 v1, s3, v0
	v_ashrrev_i32_e32 v1, 6, v1
	v_add_u32_e32 v112, s0, v1
	s_movk_i32 s9, 0x3000
	v_cmp_gt_i32_e32 vcc, s9, v112
	s_and_saveexec_b64 s[0:1], vcc
	v_readlane_b32 s20, v254, 32
	v_readlane_b32 s16, v254, 35
	v_readlane_b32 s21, v254, 33
	v_readlane_b32 s17, v254, 36
	v_readlane_b32 s18, v254, 34
	s_mul_i32 s19, s30, 24
	s_mul_i32 s21, s30, 40
	s_cbranch_execz .LBB0_694
	v_lshlrev_b32_e32 v0, 4, v0
	v_and_b32_e32 v0, 0x3f0, v0
	v_mov_b32_e32 v1, 0
	v_lshl_add_u64 v[2:3], s[28:29], 0, v[0:1]
	s_mov_b64 s[0:1], 0x217b000
	v_lshl_add_u64 v[114:115], v[2:3], 0, s[0:1]
	v_readlane_b32 s0, v254, 39
	v_readlane_b32 s1, v254, 40
	v_readlane_b32 s2, v254, 41
	v_readlane_b32 s3, v254, 42
	v_lshl_add_u64 v[116:117], s[0:1], 0, v[0:1]
	s_lshl_b32 s12, s30, 4
	v_lshl_add_u64 v[118:119], s[2:3], 0, v[0:1]
	s_lshl_b32 s13, s30, 5
	s_mov_b64 s[6:7], 0
	s_mov_b32 s8, 0x3a800000
	v_mov_b32_e32 v120, 0x358637bd
	s_mov_b32 s14, 0x800000
	s_movk_i32 s15, 0x2fff
	s_branch .LBB0_684
